# attention: loop-invariant partner-lane address and per-lane K offset/stride selects hoisted out of the tile loop
# baseline (speedup 1.0000x reference)
; __device__ __forceinline__ void attn_phase(LAS unsigned char* ldsb, bf16_t* P, const bf16_t* Kn, const bf16_t* KPE, const bf16_t* VT) {
;     ...
;             const int lane = tid & 63, w = __builtin_amdgcn_readfirstlane(tid >> 6), r = lane & 31, hh = lane >> 5;
;             const int qb = half ? 15 - jq : jq, q0 = qb * 256, nt = (q0 + 256) >> 6;
;             const int qabs = q0 + w * 32 + r;
;             bf16x8 qf[12];
;             { const bf16_t* qp = P + (rowbase + qabs) * LDP;
; #pragma unroll
;               for (int ks = 0; ks < 8; ++ks) qf[ks] = *(const bf16x8*)(qp + h * 128 + ks * 16 + hh * 8);
; #pragma unroll
;               for (int ks = 0; ks < 4; ++ks) qf[8 + ks] = *(const bf16x8*)(qp + 1024 + h * 64 + ks * 16 + hh * 8); }
;             f32x16 o[4];
; #pragma unroll
;             for (int d = 0; d < 4; ++d) for (int i = 0; i < 16; ++i) o[d][i] = 0.f;
;             float mrun = -INFINITY, lrun = 0.f;
;             u32x4 kst[3], vst[2];
;     ...
;                         const unsigned va0 = (unsigned)(size_t)(sVt + r * 68 + 4 * hh), va1 = va0 + 32 * 68 * 2, va2 = va0 + 64 * 68 * 2, va3 = va0 + 96 * 68 * 2;
.LBB0_1512:
	v_mov_b32_e32 v22, v232
	s_and_b64 s[6:7], s[76:77], exec
	v_readfirstlane_b32 s8, v22
	s_cselect_b32 s12, s33, s44
	s_ashr_i32 s6, s8, 1
	s_and_b32 s45, s6, 0xffffffe0
	v_and_b32_e32 v6, 31, v22
	s_add_i32 s45, s45, s12
	v_or_b32_e32 v228, s45, v6
	v_ashrrev_i32_e32 v229, 31, v228
	v_lshl_add_u64 v[2:3], s[60:61], 0, v[228:229]
	v_mad_u64_u32 v[226:227], s[6:7], v2, s5, v[224:225]
	v_bfe_u32 v12, v22, 5, 1
	v_mad_i32_i24 v227, v3, s5, v227
	v_lshl_add_u64 v[2:3], v[226:227], 0, s[16:17]
	v_lshlrev_b32_e32 v0, 4, v12
	v_lshl_add_u64 v[2:3], v[2:3], 0, v[0:1]
	global_load_dwordx4 v[220:223], v[2:3], off
	global_load_dwordx4 v[216:219], v[2:3], off offset:32
	global_load_dwordx4 v[212:215], v[2:3], off offset:64
	global_load_dwordx4 v[208:211], v[2:3], off offset:96
	global_load_dwordx4 v[204:207], v[2:3], off offset:128
	global_load_dwordx4 v[200:203], v[2:3], off offset:160
	global_load_dwordx4 v[196:199], v[2:3], off offset:192
	global_load_dwordx4 v[192:195], v[2:3], off offset:224
	v_lshl_add_u64 v[2:3], v[226:227], 0, s[72:73]
	v_lshl_add_u64 v[2:3], v[2:3], 0, v[0:1]
	global_load_dwordx4 v[188:191], v[2:3], off offset:2048
	global_load_dwordx4 v[184:187], v[2:3], off offset:2080
	global_load_dwordx4 v[180:183], v[2:3], off offset:2112
	global_load_dwordx4 v[176:179], v[2:3], off offset:2144
	v_mul_hi_i32 v0, v22, s20
	v_lshrrev_b32_e32 v2, 31, v0
	v_ashrrev_i32_e32 v0, 2, v0
	v_add_u32_e32 v2, v0, v2
	v_mul_lo_u32 v0, v2, 24
	v_sub_u32_e32 v23, v22, v0
	v_ashrrev_i32_e32 v3, 31, v2
	v_cmp_gt_i32_e64 s[6:7], 16, v23
	v_cmp_lt_i32_e32 vcc, 15, v23
	v_lshl_add_u64 v[10:11], s[60:61], 0, v[2:3]
	v_lshlrev_b32_e32 v4, 3, v23
	s_and_saveexec_b64 s[8:9], vcc
	s_xor_b64 s[8:9], exec, s[8:9]
	v_lshlrev_b64 v[8:9], 7, v[10:11]
	v_lshl_add_u64 v[8:9], s[14:15], 0, v[8:9]
	v_mov_b32_e32 v5, v1
	v_lshl_add_u64 v[8:9], v[4:5], 1, v[8:9]
	v_lshl_add_u64 v[8:9], v[8:9], 0, s[18:19]
	s_or_saveexec_b64 s[8:9], s[8:9]
	v_ashrrev_i32_e32 v7, 31, v4
	s_xor_b64 exec, exec, s[8:9]
	v_lshlrev_b64 v[8:9], 11, v[10:11]
	v_lshl_add_u64 v[8:9], s[64:65], 0, v[8:9]
	v_mov_b32_e32 v5, v7
	v_lshl_add_u64 v[8:9], v[4:5], 1, v[8:9]
	s_or_b64 exec, exec, s[8:9]
	global_load_dwordx4 v[112:115], v[8:9], off
	v_add_u32_e32 v24, 0x200, v22
	v_mul_hi_i32 v0, v24, s20
	v_lshrrev_b32_e32 v5, 31, v0
	v_ashrrev_i32_e32 v0, 2, v0
	v_add_u32_e32 v8, v0, v5
	v_mul_lo_u32 v0, v8, 24
	v_sub_u32_e32 v5, v24, v0
	v_ashrrev_i32_e32 v9, 31, v8
	v_cmp_gt_i32_e64 s[8:9], 16, v5
	v_cmp_lt_i32_e32 vcc, 15, v5
	v_lshl_add_u64 v[16:17], s[60:61], 0, v[8:9]
	v_lshlrev_b32_e32 v10, 3, v5
	s_and_saveexec_b64 s[10:11], vcc
	s_xor_b64 s[10:11], exec, s[10:11]
	v_lshlrev_b64 v[14:15], 7, v[16:17]
	v_lshl_add_u64 v[14:15], s[14:15], 0, v[14:15]
	v_mov_b32_e32 v11, v1
	v_lshl_add_u64 v[14:15], v[10:11], 1, v[14:15]
	v_lshl_add_u64 v[14:15], v[14:15], 0, s[18:19]
	s_or_saveexec_b64 s[10:11], s[10:11]
	v_ashrrev_i32_e32 v13, 31, v10
	s_xor_b64 exec, exec, s[10:11]
	v_lshlrev_b64 v[14:15], 11, v[16:17]
	v_lshl_add_u64 v[14:15], s[64:65], 0, v[14:15]
	v_mov_b32_e32 v11, v13
	v_lshl_add_u64 v[14:15], v[10:11], 1, v[14:15]
	s_or_b64 exec, exec, s[10:11]
	global_load_dwordx4 v[116:119], v[14:15], off
	v_add_u32_e32 v0, 0x400, v22
	v_mul_hi_i32 v11, v0, s20
	v_lshrrev_b32_e32 v14, 31, v11
	v_ashrrev_i32_e32 v11, 2, v11
	v_add_u32_e32 v14, v11, v14
	v_mul_lo_u32 v11, v14, 24
	v_sub_u32_e32 v11, v0, v11
	v_ashrrev_i32_e32 v15, 31, v14
	v_cmp_gt_i32_e64 s[10:11], 16, v11
	v_cmp_lt_i32_e32 vcc, 15, v11
	v_lshl_add_u64 v[20:21], s[60:61], 0, v[14:15]
	v_lshlrev_b32_e32 v0, 3, v11
	s_and_saveexec_b64 s[34:35], vcc
	s_xor_b64 s[74:75], exec, s[34:35]
	v_lshlrev_b64 v[16:17], 7, v[20:21]
	v_lshl_add_u64 v[16:17], s[14:15], 0, v[16:17]
	v_lshl_add_u64 v[16:17], v[0:1], 1, v[16:17]
	v_lshl_add_u64 v[18:19], v[16:17], 0, s[18:19]
	s_or_saveexec_b64 s[74:75], s[74:75]
	v_mov_b64_e32 v[16:17], v[0:1]
	s_xor_b64 exec, exec, s[74:75]
	v_lshlrev_b64 v[16:17], 11, v[20:21]
	v_lshl_add_u64 v[18:19], s[64:65], 0, v[16:17]
	v_ashrrev_i32_e32 v17, 31, v0
	v_mov_b32_e32 v16, v0
	v_lshl_add_u64 v[18:19], v[16:17], 1, v[18:19]
	s_or_b64 exec, exec, s[74:75]
	global_load_dwordx4 v[120:123], v[18:19], off
	v_lshlrev_b32_e32 v18, 4, v22
	v_ashrrev_i32_e32 v26, 3, v22
	v_and_b32_e32 v18, 0x70, v18
	v_mov_b32_e32 v19, v1
	v_ashrrev_i32_e32 v27, 31, v26
	v_ashrrev_i32_e32 v24, 3, v24
	v_lshl_add_u64 v[20:21], s[62:63], 0, v[18:19]
	v_lshlrev_b64 v[28:29], 13, v[26:27]
	v_ashrrev_i32_e32 v25, 31, v24
	v_lshl_add_u64 v[30:31], v[20:21], 0, v[28:29]
	v_lshlrev_b64 v[32:33], 13, v[24:25]
	v_lshl_add_u64 v[20:21], v[20:21], 0, v[32:33]
	global_load_dwordx4 v[128:131], v[30:31], off
	global_load_dwordx4 v[124:127], v[20:21], off
	v_lshlrev_b32_e32 v34, 3, v12
	v_add_u32_e32 v25, 0, v18
	v_mad_u32_u24 v18, v6, s21, 0
; #define LAS __attribute__((address_space(3)))
; __device__ __forceinline__ void attn_phase(LAS unsigned char* ldsb, bf16_t* P, const bf16_t* Kn, const bf16_t* KPE, const bf16_t* VT) {
;     ...
;             f32x16 o[4];
; #pragma unroll
;             for (int d = 0; d < 4; ++d) for (int i = 0; i < 16; ++i) o[d][i] = 0.f;
;             float mrun = -INFINITY, lrun = 0.f;
;             u32x4 kst[3], vst[2];
;     ...
;             ATT_LOAD(0);
;             for (int kt = 0; kt < nt; ++kt) {
;                 __syncthreads();
; #pragma unroll
;                 for (int i = 0; i < 3; ++i) { const int id = tid + 512 * i, row = id / 24, ch = id % 24; *(LAS u32x4*)(sK + row * 200 + ch * 8) = kst[i]; }
; #pragma unroll
;                 for (int i = 0; i < 2; ++i) { const int id = tid + 512 * i, d = id >> 3, ch = id & 7;
;                     *(LAS u32x2*)(sVt + d * 68 + ch * 8) = (u32x2){vst[i].x, vst[i].y}; *(LAS u32x2*)(sVt + d * 68 + ch * 8 + 4) = (u32x2){vst[i].z, vst[i].w}; }
;                 __syncthreads();
;                 if (kt + 1 < nt) ATT_LOAD(kt + 1);
;     ...
;                     mx = fmaxf(mx, __shfl_xor(mx, 32));
	v_mul_i32_i24_e32 v6, 0xfffffef8, v6
	v_and_b32_e32 v20, 7, v22
	v_lshl_add_u32 v241, v12, 4, v18
	v_add3_u32 v6, v18, v6, v34
	v_lshl_add_u64 v[18:19], s[66:67], 0, v[28:29]
	v_lshlrev_b32_e32 v20, 4, v20
	v_mov_b32_e32 v21, v1
	v_add_u32_e32 v239, 0x6400, v6
	v_add_u32_e32 v238, 0x7500, v6
	v_add_u32_e32 v237, 0x8600, v6
	v_add_u32_e32 v235, 0x9700, v6
	v_mul_lo_u32 v6, v2, s21
	v_lshl_add_u64 v[132:133], v[18:19], 0, v[20:21]
	v_lshl_add_u64 v[18:19], s[66:67], 0, v[32:33]
	v_add_u32_e32 v27, 0, v6
	v_mul_lo_u32 v6, v8, s21
	v_lshl_add_u64 v[134:135], v[18:19], 0, v[20:21]
	v_lshlrev_b64 v[18:19], 7, v[2:3]
	v_lshlrev_b64 v[2:3], 11, v[2:3]
	v_add_u32_e32 v30, 0, v6
	v_mov_b32_e32 v6, v4
	v_lshl_add_u64 v[2:3], s[70:71], 0, v[2:3]
	v_lshl_add_u64 v[138:139], v[6:7], 1, v[2:3]
	v_lshlrev_b64 v[2:3], 7, v[8:9]
	v_lshlrev_b32_e32 v35, 4, v11
	v_mov_b32_e32 v11, v1
	v_lshl_add_u64 v[2:3], s[68:69], 0, v[2:3]
	v_lshl_add_u64 v[140:141], v[10:11], 1, v[2:3]
	v_lshlrev_b64 v[2:3], 11, v[8:9]
	v_lshlrev_b32_e32 v229, 2, v12
	v_mov_b32_e32 v12, v10
	v_lshl_add_u64 v[2:3], s[70:71], 0, v[2:3]
	v_lshl_add_u64 v[142:143], v[12:13], 1, v[2:3]
	v_lshlrev_b64 v[2:3], 7, v[14:15]
	v_lshl_add_u64 v[2:3], s[68:69], 0, v[2:3]
	v_lshlrev_b32_e32 v31, 4, v5
	v_mul_lo_u32 v5, v14, s21
	v_lshl_add_u64 v[144:145], v[0:1], 1, v[2:3]
	v_lshlrev_b64 v[2:3], 11, v[14:15]
	s_addk_i32 s12, 0x100
	v_lshlrev_b32_e32 v23, 4, v23
	v_add_u32_e32 v34, 0, v5
	v_mul_lo_u32 v26, v26, s30
	v_mul_lo_u32 v24, v24, s30
	v_mov_b32_e32 v5, v1
	v_lshl_add_u64 v[18:19], s[68:69], 0, v[18:19]
	v_lshl_add_u64 v[2:3], s[70:71], 0, v[2:3]
	v_mov_b32_e32 v14, v1
	v_mov_b32_e32 v15, v1
	s_lshr_b32 s12, s12, 6
	v_lshl_add_u64 v[136:137], v[4:5], 1, v[18:19]
	v_lshl_add_u64 v[146:147], v[16:17], 1, v[2:3]
	v_mov_b32_e32 v0, v1
	v_mov_b32_e32 v2, v1
	v_mov_b32_e32 v3, v1
	v_mov_b32_e32 v4, v1
	v_mov_b32_e32 v6, v1
	v_mov_b32_e32 v7, v1
	v_mov_b32_e32 v8, v1
	v_mov_b32_e32 v9, v1
	v_mov_b32_e32 v10, v1
	v_mov_b32_e32 v12, v1
	v_mov_b32_e32 v13, v1
	v_add_u32_e32 v148, v27, v23
	v_add_u32_e32 v149, v30, v31
	v_add_u32_e32 v150, v34, v35
	v_add3_u32 v151, v25, v26, s29
	v_add3_u32 v152, v25, v24, s29
	v_mov_b64_e32 v[30:31], v[14:15]
	v_mov_b64_e32 v[46:47], v[14:15]
	v_mov_b64_e32 v[62:63], v[14:15]
	v_mov_b64_e32 v[78:79], v[14:15]
	s_xor_b64 s[74:75], s[76:77], -1
	s_or_b32 s76, s45, 31
	s_add_i32 s77, s12, -1
	v_mov_b32_e32 v240, 0xff800000
	v_mov_b32_e32 v236, 0
	s_mov_b32 s78, 63
	v_mov_b64_e32 v[28:29], v[12:13]
	v_mov_b64_e32 v[26:27], v[10:11]
	v_mov_b64_e32 v[24:25], v[8:9]
	v_mov_b64_e32 v[22:23], v[6:7]
	v_mov_b64_e32 v[20:21], v[4:5]
	v_mov_b64_e32 v[18:19], v[2:3]
	v_mov_b64_e32 v[16:17], v[0:1]
	v_mov_b64_e32 v[44:45], v[12:13]
	v_mov_b64_e32 v[42:43], v[10:11]
	v_mov_b64_e32 v[40:41], v[8:9]
	v_mov_b64_e32 v[38:39], v[6:7]
	v_mov_b64_e32 v[36:37], v[4:5]
	v_mov_b64_e32 v[34:35], v[2:3]
	v_mov_b64_e32 v[32:33], v[0:1]
	v_mov_b64_e32 v[60:61], v[12:13]
	v_mov_b64_e32 v[58:59], v[10:11]
	v_mov_b64_e32 v[56:57], v[8:9]
	v_mov_b64_e32 v[54:55], v[6:7]
	v_mov_b64_e32 v[52:53], v[4:5]
	v_mov_b64_e32 v[50:51], v[2:3]
	v_mov_b64_e32 v[48:49], v[0:1]
	v_mov_b64_e32 v[76:77], v[12:13]
	v_mov_b64_e32 v[74:75], v[10:11]
	v_mov_b64_e32 v[72:73], v[8:9]
	v_mov_b64_e32 v[70:71], v[6:7]
	v_mov_b64_e32 v[68:69], v[4:5]
	v_mov_b64_e32 v[66:67], v[2:3]
	v_mov_b64_e32 v[64:65], v[0:1]
	s_barrier
	v_and_b32_e32 v3, 64, v234
	v_xor_b32_e32 v2, 32, v234
	v_add_u32_e32 v3, 64, v3
	v_cmp_lt_i32_e32 vcc, v2, v3
	v_mov_b32_e32 v4, 0x2000
	v_mov_b32_e32 v5, 0x20000
	v_cndmask_b32_e32 v2, v234, v2, vcc
	v_lshlrev_b32_e32 v174, 2, v2
	v_cndmask_b32_e64 v136, v136, v138, s[6:7]
	v_cndmask_b32_e64 v138, v4, v5, s[6:7]
	v_cndmask_b32_e64 v140, v140, v142, s[8:9]
	v_cndmask_b32_e64 v142, v4, v5, s[8:9]
	v_cndmask_b32_e64 v144, v144, v146, s[10:11]
	v_cndmask_b32_e64 v146, v4, v5, s[10:11]
	s_waitcnt vmcnt(4)
	ds_write_b128 v148, v[112:115]
	s_waitcnt vmcnt(3)
	ds_write_b128 v149, v[116:119]
	s_waitcnt vmcnt(2)
	ds_write_b128 v150, v[120:123]
	s_waitcnt vmcnt(1)
	ds_write2_b64 v151, v[128:129], v[130:131] offset1:1
	s_waitcnt vmcnt(0)
	ds_write2_b64 v152, v[124:125], v[126:127] offset1:1
	s_waitcnt lgkmcnt(0)
	s_barrier
	global_load_dwordx4 v[112:115], v136, s[26:27]
	global_load_dwordx4 v[116:119], v140, s[26:27]
	global_load_dwordx4 v[120:123], v144, s[26:27]
	global_load_dwordx4 v[128:131], v132, s[26:27]
	global_load_dwordx4 v[124:127], v134, s[26:27]
	v_add_u32_e32 v132, 0x80, v132
	v_add_u32_e32 v134, 0x80, v134
	v_add_u32_e32 v136, v136, v138
	v_add_u32_e32 v140, v140, v142
	v_add_u32_e32 v144, v144, v146
	v_xor_b32_e32 v148, 0x10000, v148
	v_xor_b32_e32 v149, 0x10000, v149
	v_xor_b32_e32 v150, 0x10000, v150
	v_xor_b32_e32 v151, 0x10000, v151
	v_xor_b32_e32 v152, 0x10000, v152
	s_branch .LBB0_1527

; #define LAS __attribute__((address_space(3)))
; __device__ __forceinline__ void attn_phase(LAS unsigned char* ldsb, bf16_t* P, const bf16_t* Kn, const bf16_t* KPE, const bf16_t* VT) {
;     ...
;             for (int kt = 0; kt < nt; ++kt) {
;                 __syncthreads();
; #pragma unroll
;                 for (int i = 0; i < 3; ++i) { const int id = tid + 512 * i, row = id / 24, ch = id % 24; *(LAS u32x4*)(sK + row * 200 + ch * 8) = kst[i]; }
; #pragma unroll
;                 for (int i = 0; i < 2; ++i) { const int id = tid + 512 * i, d = id >> 3, ch = id & 7;
;                     *(LAS u32x2*)(sVt + d * 68 + ch * 8) = (u32x2){vst[i].x, vst[i].y}; *(LAS u32x2*)(sVt + d * 68 + ch * 8 + 4) = (u32x2){vst[i].z, vst[i].w}; }
;                 __syncthreads();
;                 if (kt + 1 < nt) ATT_LOAD(kt + 1);
.LBB0_1527:
	s_cmp_lt_u32 s77, 2
	s_cbranch_scc1 .Lattn_nopre
	s_waitcnt vmcnt(4)
	ds_write_b128 v148, v[112:115]
	s_waitcnt vmcnt(3)
	ds_write_b128 v149, v[116:119]
	s_waitcnt vmcnt(2)
	ds_write_b128 v150, v[120:123]
	s_waitcnt vmcnt(1)
	ds_write2_b64 v151, v[128:129], v[130:131] offset1:1
	s_waitcnt vmcnt(0)
	ds_write2_b64 v152, v[124:125], v[126:127] offset1:1
	s_waitcnt lgkmcnt(0)
	global_load_dwordx4 v[112:115], v136, s[26:27]
	global_load_dwordx4 v[116:119], v140, s[26:27]
	global_load_dwordx4 v[120:123], v144, s[26:27]
	global_load_dwordx4 v[128:131], v132, s[26:27]
	global_load_dwordx4 v[124:127], v134, s[26:27]
	v_add_u32_e32 v132, 0x80, v132
	v_add_u32_e32 v134, 0x80, v134
	v_add_u32_e32 v136, v136, v138
	v_add_u32_e32 v140, v140, v142
	v_add_u32_e32 v144, v144, v146

; __device__ __forceinline__ void attn_phase(LAS unsigned char* ldsb, bf16_t* P, const bf16_t* Kn, const bf16_t* KPE, const bf16_t* VT) {
;     ...
;                     float mx = st[0][0];
; #pragma unroll
;                     for (int kb = 0; kb < 2; ++kb)
; #pragma unroll
;                         for (int i = 0; i < 16; ++i) mx = fmaxf(mx, st[kb][i]);
;                     mx = fmaxf(mx, __shfl_xor(mx, 32));
;                     if (__builtin_amdgcn_ballot_w64(mx > mrun) != 0ull) {
;                         const float mnew = fmaxf(mrun, mx);
;                         const float alpha = __builtin_amdgcn_exp2f(mrun - mnew);
;                         mrun = mnew; lrun *= alpha;
; #pragma unroll
;                         for (int d = 0; d < 4; ++d)
; #pragma unroll
;                             for (int i = 0; i < 16; ++i) o[d][i] *= alpha;
;                     }
.LBB0_1530:
	ds_read2_b64 v[154:157], v239 offset0:0 offset1:2
	ds_read2_b64 v[158:161], v238 offset0:0 offset1:2
	ds_read2_b64 v[162:165], v237 offset0:0 offset1:2
	ds_read2_b64 v[166:169], v235 offset0:0 offset1:2
	ds_read2_b64 v[170:173], v239 offset0:4 offset1:6
	ds_read2_b64 v[244:247], v238 offset0:4 offset1:6
	ds_read2_b64 v[248:251], v237 offset0:4 offset1:6
	ds_read2_b64 v[252:255], v235 offset0:4 offset1:6
	s_nop 1
	v_max_f32_e32 v0, v97, v97
	v_max_f32_e32 v2, v96, v96
	v_max_f32_e32 v0, v2, v0
	v_max3_f32 v0, v0, v98, v99
	v_max3_f32 v0, v0, v100, v101
	v_max3_f32 v0, v0, v102, v103
	v_max3_f32 v0, v0, v104, v105
	v_max3_f32 v0, v0, v106, v107
	v_max3_f32 v0, v0, v108, v109
	v_max3_f32 v0, v0, v110, v111
	v_max3_f32 v0, v0, v80, v81
	v_max3_f32 v0, v0, v82, v83
	v_max3_f32 v0, v0, v84, v85
	v_max3_f32 v0, v0, v86, v87
	v_max3_f32 v0, v0, v88, v89
	v_max3_f32 v0, v0, v90, v91
	v_max3_f32 v0, v0, v92, v93
	v_max3_f32 v0, v0, v94, v95
	s_nop 0
	ds_bpermute_b32 v2, v174, v0
	s_waitcnt lgkmcnt(0)
	v_max_f32_e32 v2, v2, v2
	v_max_f32_e32 v0, v0, v2
	v_sub_f32_e32 v2, v0, v240
	v_cmp_lt_f32_e32 vcc, 4.0, v2
	s_cbranch_vccz .LBB0_1525
	v_max_f32_e32 v0, v0, v0
	v_max_f32_e32 v2, v240, v240
	v_max_f32_e32 v2, v2, v0
	v_sub_f32_e32 v0, v240, v2
	v_exp_f32_e32 v0, v0
	v_mov_b32_e32 v240, v2
	v_pk_mul_f32 v[78:79], v[78:79], v[0:1] op_sel_hi:[1,0]
	v_pk_mul_f32 v[76:77], v[76:77], v[0:1] op_sel_hi:[1,0]
	v_pk_mul_f32 v[74:75], v[74:75], v[0:1] op_sel_hi:[1,0]
	v_pk_mul_f32 v[72:73], v[72:73], v[0:1] op_sel_hi:[1,0]
	v_pk_mul_f32 v[70:71], v[70:71], v[0:1] op_sel_hi:[1,0]
	v_pk_mul_f32 v[68:69], v[68:69], v[0:1] op_sel_hi:[1,0]
	v_pk_mul_f32 v[66:67], v[66:67], v[0:1] op_sel_hi:[1,0]
	v_pk_mul_f32 v[64:65], v[64:65], v[0:1] op_sel_hi:[1,0]
	v_pk_mul_f32 v[62:63], v[62:63], v[0:1] op_sel_hi:[1,0]
	v_pk_mul_f32 v[60:61], v[60:61], v[0:1] op_sel_hi:[1,0]
	v_pk_mul_f32 v[58:59], v[58:59], v[0:1] op_sel_hi:[1,0]
	v_pk_mul_f32 v[56:57], v[56:57], v[0:1] op_sel_hi:[1,0]
	v_pk_mul_f32 v[54:55], v[54:55], v[0:1] op_sel_hi:[1,0]
	v_pk_mul_f32 v[52:53], v[52:53], v[0:1] op_sel_hi:[1,0]
	v_pk_mul_f32 v[50:51], v[50:51], v[0:1] op_sel_hi:[1,0]
	v_pk_mul_f32 v[48:49], v[48:49], v[0:1] op_sel_hi:[1,0]
	v_pk_mul_f32 v[46:47], v[46:47], v[0:1] op_sel_hi:[1,0]
	v_pk_mul_f32 v[44:45], v[44:45], v[0:1] op_sel_hi:[1,0]
	v_pk_mul_f32 v[42:43], v[42:43], v[0:1] op_sel_hi:[1,0]
	v_pk_mul_f32 v[40:41], v[40:41], v[0:1] op_sel_hi:[1,0]
	v_pk_mul_f32 v[38:39], v[38:39], v[0:1] op_sel_hi:[1,0]
	v_pk_mul_f32 v[36:37], v[36:37], v[0:1] op_sel_hi:[1,0]
	v_pk_mul_f32 v[34:35], v[34:35], v[0:1] op_sel_hi:[1,0]
	v_pk_mul_f32 v[32:33], v[32:33], v[0:1] op_sel_hi:[1,0]
	v_pk_mul_f32 v[30:31], v[30:31], v[0:1] op_sel_hi:[1,0]
	v_pk_mul_f32 v[28:29], v[28:29], v[0:1] op_sel_hi:[1,0]
	v_pk_mul_f32 v[26:27], v[26:27], v[0:1] op_sel_hi:[1,0]
	v_pk_mul_f32 v[24:25], v[24:25], v[0:1] op_sel_hi:[1,0]
	v_pk_mul_f32 v[22:23], v[22:23], v[0:1] op_sel_hi:[1,0]
	v_pk_mul_f32 v[20:21], v[20:21], v[0:1] op_sel_hi:[1,0]
	v_pk_mul_f32 v[18:19], v[18:19], v[0:1] op_sel_hi:[1,0]
	v_pk_mul_f32 v[16:17], v[16:17], v[0:1] op_sel_hi:[1,0]
	v_mul_f32_e32 v236, v236, v0
	s_branch .LBB0_1525
